# XCD barrier: acquire-side buffer_inv issued at arrival instead of after release (plus scan1 rewrite, OWN combine, cg split)
# speedup vs baseline: 1.0080x; 1.0080x over previous
.LBB0_1024:
	s_waitcnt vmcnt(0)
	s_waitcnt vmcnt(0) lgkmcnt(0)
	s_barrier
	s_and_saveexec_b64 s[6:7], s[52:53]
	s_cbranch_execz .LBB0_1078
	buffer_inv sc1
	v_readlane_b32 s1, v255, 10
	s_getreg_b32 s0, hwreg(HW_REG_XCC_ID, 0, 4)
	s_waitcnt vmcnt(0) expcnt(0) lgkmcnt(0)
	v_mov_b32_e32 v0, s1
	ds_read_b32 v2, v0
	v_readlane_b32 s1, v255, 11
	s_and_b32 s0, s0, 15
	s_waitcnt lgkmcnt(0)
	v_cmp_ne_u32_e32 vcc, 0, v2
	v_mov_b32_e32 v0, s1
	ds_read_b32 v0, v0
	s_cbranch_vccnz .LBB0_1042
	s_add_u32 s8, s90, 0x494b200
	s_addc_u32 s9, s91, 0
	s_add_u32 s10, s90, 0x494b400
	s_addc_u32 s11, s91, 0
	s_add_u32 s12, s90, 0x494b500
	s_addc_u32 s13, s91, 0
	s_add_u32 s16, s90, 0x494b600
	s_addc_u32 s17, s91, 0
	s_add_u32 s18, s90, 0x494b700
	s_addc_u32 s19, s91, 0
	s_add_u32 s20, s90, 0x494b800
	s_addc_u32 s21, s91, 0
	s_add_u32 s22, s90, 0x494b900
	s_addc_u32 s23, s91, 0
	s_add_u32 s24, s90, 0x494ba00
	s_addc_u32 s25, s91, 0
	s_add_u32 s28, s90, 0x494bb00
	s_addc_u32 s29, s91, 0
	s_add_u32 s36, s90, 0x494bc00
	s_addc_u32 s37, s91, 0
	s_add_u32 s58, s90, 0x494bd00
	s_addc_u32 s59, s91, 0
	s_add_u32 s62, s90, 0x494be00
	s_addc_u32 s63, s91, 0
	s_add_u32 s66, s90, 0x494bf00
	s_addc_u32 s67, s91, 0
	s_add_u32 s72, s90, 0x494c000
	s_addc_u32 s73, s91, 0
	s_add_u32 s74, s90, 0x494c100
	s_addc_u32 s75, s91, 0
	s_add_u32 s88, s90, 0x494c200
	s_addc_u32 s89, s91, 0
	s_add_u32 s92, s90, 0x494c300
	s_addc_u32 s93, s91, 0
	s_mov_b32 s4, 1
	s_branch .LBB0_1028

.LBB0_1057:
	s_or_b64 exec, exec, s[12:13]
	s_waitcnt vmcnt(0)
	s_waitcnt vmcnt(0)

.LBB0_1075:
	s_or_b64 exec, exec, s[10:11]
	s_mov_b64 s[10:11], exec
	v_mbcnt_lo_u32_b32 v0, s10, 0
	v_mbcnt_hi_u32_b32 v0, s11, v0
	v_cmp_eq_u32_e32 vcc, 0, v0
	s_waitcnt vmcnt(0)
	s_and_saveexec_b64 s[12:13], vcc
	s_cbranch_execz .LBB0_1077
	s_bcnt1_i32_b64 s0, s[10:11]
	v_mov_b32_e32 v0, s0
	v_mov_b32_e32 v1, 0x2000
	global_atomic_add v1, v0, s[8:9] offset:1024
